# v35 with the MLA QK groups in S0 S1 S1 S0 order (pairs straddle the group boundaries)
# baseline (speedup 1.0000x reference)
.LBB0_2904:
	v_add_u32_e32 v0, s28, v183
	ds_read_b128 v[2:5], v0 offset:24576
	ds_read_b128 v[6:9], v0 offset:28672
	ds_read_b128 v[10:13], v0 offset:32768
	ds_read_b128 v[184:187], v0 offset:36864
	v_exp_f32_e32 v14, v96
	v_exp_f32_e32 v190, v97
	v_exp_f32_e32 v98, v98
	v_exp_f32_e32 v192, v99
	v_exp_f32_e32 v15, v100
	v_exp_f32_e32 v191, v101
	v_exp_f32_e32 v99, v102
	v_exp_f32_e32 v193, v103
	v_add_u32_e32 v0, s28, v182
	v_pk_add_f32 v[96:97], v[14:15], v[190:191]
	v_pk_add_f32 v[100:101], v[98:99], v[192:193]
	s_nop 0
	v_pk_add_f32 v[96:97], v[96:97], v[100:101]
	v_cvt_pk_bf16_f32 v99, v99, v193
	v_pk_add_f32 v[202:203], v[96:97], v[96:97] op_sel_hi:[0,1]
	v_cvt_pk_bf16_f32 v96, v14, v190
	v_cvt_pk_bf16_f32 v97, v98, v192
	v_cvt_pk_bf16_f32 v98, v15, v191
	ds_read_b128 v[100:103], v0 offset:24576
	ds_read_b128 v[190:193], v0 offset:28672
	ds_read_b128 v[194:197], v0 offset:32768
	ds_read_b128 v[198:201], v0 offset:36864
	s_waitcnt lgkmcnt(0)
	v_mfma_f32_32x32x16_bf16 v[64:79], v[2:5], v[96:99], v[64:79]
	v_mfma_f32_32x32x16_bf16 v[48:63], v[6:9], v[96:99], v[48:63]
	v_mfma_f32_32x32x16_bf16 v[32:47], v[10:13], v[96:99], v[32:47]
	v_mfma_f32_32x32x16_bf16 v[16:31], v[184:187], v[96:99], v[16:31]
	v_exp_f32_e32 v2, v104
	v_exp_f32_e32 v4, v105
	v_exp_f32_e32 v3, v106
	v_exp_f32_e32 v5, v107
	v_exp_f32_e32 v6, v108
	v_exp_f32_e32 v8, v109
	v_exp_f32_e32 v7, v110
	v_exp_f32_e32 v9, v111
	v_pk_add_f32 v[10:11], v[2:3], v[4:5]
	v_add_u32_e32 v0, s28, v180
	v_pk_add_f32 v[14:15], v[10:11], v[10:11] op_sel_hi:[0,1]
	v_pk_add_f32 v[10:11], v[6:7], v[8:9]
	v_cvt_pk_bf16_f32 v2, v2, v4
	v_pk_add_f32 v[184:185], v[10:11], v[10:11] op_sel_hi:[0,1]
	v_cvt_pk_bf16_f32 v3, v3, v5
	v_cvt_pk_bf16_f32 v4, v6, v8
	v_cvt_pk_bf16_f32 v5, v7, v9
	ds_read_b128 v[6:9], v0 offset:24576
	ds_read_b128 v[10:13], v0 offset:28672
	ds_read_b128 v[96:99], v0 offset:32768
	ds_read_b128 v[104:107], v0 offset:36864
	v_mfma_f32_32x32x16_bf16 v[64:79], v[100:103], v[2:5], v[64:79]
	v_mfma_f32_32x32x16_bf16 v[48:63], v[190:193], v[2:5], v[48:63]
	v_mfma_f32_32x32x16_bf16 v[32:47], v[194:197], v[2:5], v[32:47]
	v_mfma_f32_32x32x16_bf16 v[16:31], v[198:201], v[2:5], v[16:31]
	v_exp_f32_e32 v0, v80
	v_exp_f32_e32 v2, v81
	v_exp_f32_e32 v3, v82
	v_exp_f32_e32 v4, v83
	v_exp_f32_e32 v5, v84
	v_exp_f32_e32 v14, v85
	v_exp_f32_e32 v80, v86
	v_exp_f32_e32 v81, v87
	v_add_f32_e32 v187, v0, v2
	v_cvt_pk_bf16_f32 v2, v0, v2
	v_add_u32_e32 v0, s28, v175
	v_add_f32_e32 v191, v3, v4
	v_add_f32_e32 v193, v5, v14
	v_add_f32_e32 v195, v80, v81
	v_cvt_pk_bf16_f32 v3, v3, v4
	v_cvt_pk_bf16_f32 v4, v5, v14
	v_cvt_pk_bf16_f32 v5, v80, v81
	ds_read_b128 v[80:83], v0 offset:24576
	ds_read_b128 v[84:87], v0 offset:28672
	ds_read_b128 v[100:103], v0 offset:32768
	ds_read_b128 v[108:111], v0 offset:36864
	s_waitcnt lgkmcnt(0)
	v_mfma_f32_32x32x16_bf16 v[64:79], v[6:9], v[2:5], v[64:79]
	v_mfma_f32_32x32x16_bf16 v[48:63], v[10:13], v[2:5], v[48:63]
	v_mfma_f32_32x32x16_bf16 v[32:47], v[96:99], v[2:5], v[32:47]
	v_mfma_f32_32x32x16_bf16 v[16:31], v[104:107], v[2:5], v[16:31]
	v_exp_f32_e32 v186, v88
	v_exp_f32_e32 v190, v89
	v_exp_f32_e32 v192, v90
	v_exp_f32_e32 v194, v91
	v_exp_f32_e32 v14, v92
	v_exp_f32_e32 v184, v93
	v_exp_f32_e32 v202, v94
	v_exp_f32_e32 v0, v95
	v_cvt_pk_bf16_f32 v2, v186, v190
	v_cvt_pk_bf16_f32 v3, v192, v194
	v_cvt_pk_bf16_f32 v4, v14, v184
	v_cvt_pk_bf16_f32 v5, v202, v0
	s_nop 1
	v_mfma_f32_32x32x16_bf16 v[64:79], v[80:83], v[2:5], v[64:79]
	v_add_f32_e64 v6, v186, v190
	v_add_f32_e64 v7, v187, v191
	v_add_f32_e64 v8, v192, v194
	v_add_f32_e64 v9, v193, v195
	v_add_f32_e64 v10, v202, v0
	v_add_f32_e64 v11, v203, v1
	v_pk_add_f32 v[6:7], v[6:7], v[8:9]
	v_pk_add_f32 v[8:9], v[14:15], v[184:185]
	s_nop 0
	v_pk_add_f32 v[8:9], v[8:9], v[10:11]
	v_mfma_f32_32x32x16_bf16 v[48:63], v[84:87], v[2:5], v[48:63]
	v_add_f32_e64 v6, v6, v8
	v_add_f32_e64 v7, v7, v9
	v_pk_add_f32 v[6:7], v[6:7], v[6:7] op_sel:[0,1] op_sel_hi:[1,0]
	v_mfma_f32_32x32x16_bf16 v[32:47], v[100:103], v[2:5], v[32:47]
	v_mfma_f32_32x32x16_bf16 v[16:31], v[108:111], v[2:5], v[16:31]
	v_mov_b32_e32 v0, v6
	s_nop 1
	v_permlane32_swap_b32_e32 v6, v0
	v_add_f32_e32 v0, v6, v0
	v_add_f32_e32 v171, v171, v0
	v_add_u32_e32 v0, s1, v174
	v_add_u32_e32 v14, s1, v173
	v_add_u32_e32 v15, s1, v170
	ds_read_b128 v[2:5], v0
	ds_read_b128 v[6:9], v0 offset:12288
	ds_read_b128 v[10:13], v14
	ds_read_b128 v[184:187], v14 offset:12288
	v_add_u32_e32 v206, s1, v172
	ds_read_b128 v[190:193], v15
	ds_read_b128 v[194:197], v15 offset:12288
	ds_read_b128 v[198:201], v206
	ds_read_b128 v[202:205], v206 offset:12288
	v_xor_b32_e32 v80, 0x80000000, v181
	v_mov_b32_e32 v81, v80
	v_mov_b32_e32 v82, v80
	v_mov_b32_e32 v83, v80
	v_mov_b32_e32 v84, v80
	v_mov_b32_e32 v85, v80
	v_mov_b32_e32 v86, v80
	v_mov_b32_e32 v87, v80
	v_mov_b32_e32 v88, v80
	v_mov_b32_e32 v89, v80
	v_mov_b32_e32 v90, v80
	v_mov_b32_e32 v91, v80
	v_mov_b32_e32 v92, v80
	v_mov_b32_e32 v93, v80
	v_mov_b32_e32 v94, v80
	v_mov_b32_e32 v95, v80
	s_waitcnt lgkmcnt(0)
	s_nop 0
	v_mfma_f32_32x32x16_bf16 v[96:111], v[2:5], v[112:115], v[80:95]
	v_mfma_f32_32x32x16_bf16 v[80:95], v[6:9], v[112:115], v[80:95]
	v_mfma_f32_32x32x16_bf16 v[80:95], v[184:187], v[116:119], v[80:95]
	v_mfma_f32_32x32x16_bf16 v[96:111], v[10:13], v[116:119], v[96:111]
	ds_read_b128 v[2:5], v14 offset:12416
	ds_read_b128 v[6:9], v14 offset:128
	ds_read_b128 v[10:13], v0 offset:12416
	ds_read_b128 v[184:187], v0 offset:128
	v_mfma_f32_32x32x16_bf16 v[96:111], v[190:193], v[120:123], v[96:111]
	v_mfma_f32_32x32x16_bf16 v[80:95], v[194:197], v[120:123], v[80:95]
	v_mfma_f32_32x32x16_bf16 v[80:95], v[202:205], v[124:127], v[80:95]
	v_mfma_f32_32x32x16_bf16 v[96:111], v[198:201], v[124:127], v[96:111]
	ds_read_b128 v[190:193], v15 offset:128
	ds_read_b128 v[194:197], v15 offset:12416
	ds_read_b128 v[198:201], v206 offset:128
	ds_read_b128 v[202:205], v206 offset:12416
	s_waitcnt lgkmcnt(0)
	v_mfma_f32_32x32x16_bf16 v[96:111], v[184:187], v[128:131], v[96:111]
	v_mfma_f32_32x32x16_bf16 v[80:95], v[10:13], v[128:131], v[80:95]
	v_mfma_f32_32x32x16_bf16 v[80:95], v[2:5], v[132:135], v[80:95]
	v_mfma_f32_32x32x16_bf16 v[96:111], v[6:9], v[132:135], v[96:111]
	ds_read_b128 v[2:5], v14 offset:12544
	ds_read_b128 v[6:9], v14 offset:256
	ds_read_b128 v[10:13], v0 offset:12544
	ds_read_b128 v[184:187], v0 offset:256
	v_mfma_f32_32x32x16_bf16 v[96:111], v[190:193], v[136:139], v[96:111]
	v_mfma_f32_32x32x16_bf16 v[80:95], v[194:197], v[136:139], v[80:95]
	v_mfma_f32_32x32x16_bf16 v[80:95], v[202:205], v[140:143], v[80:95]
	v_mfma_f32_32x32x16_bf16 v[96:111], v[198:201], v[140:143], v[96:111]
	ds_read_b128 v[190:193], v15 offset:256
	ds_read_b128 v[194:197], v15 offset:12544
	ds_read_b128 v[198:201], v206 offset:256
	ds_read_b128 v[202:205], v206 offset:12544
	s_waitcnt lgkmcnt(0)
	v_mfma_f32_32x32x16_bf16 v[96:111], v[184:187], v[144:147], v[96:111]
	v_mfma_f32_32x32x16_bf16 v[80:95], v[10:13], v[144:147], v[80:95]
	v_mfma_f32_32x32x16_bf16 v[80:95], v[2:5], v[148:151], v[80:95]
	v_mfma_f32_32x32x16_bf16 v[96:111], v[6:9], v[148:151], v[96:111]
	v_mfma_f32_32x32x16_bf16 v[96:111], v[190:193], v[152:155], v[96:111]
	v_mfma_f32_32x32x16_bf16 v[96:111], v[198:201], v[156:159], v[96:111]
	v_mfma_f32_32x32x16_bf16 v[80:95], v[194:197], v[152:155], v[80:95]
	s_nop 10
	v_max_f32_e32 v0, v97, v97
	v_max_f32_e32 v2, v96, v96
	v_max_f32_e32 v0, v2, v0
	v_max3_f32 v0, v0, v98, v99
	v_max3_f32 v0, v0, v100, v101
	v_max3_f32 v0, v0, v102, v103
	v_max3_f32 v0, v0, v104, v105
	v_mfma_f32_32x32x16_bf16 v[80:95], v[202:205], v[156:159], v[80:95]
	v_max3_f32 v0, v0, v106, v107
	v_max3_f32 v0, v0, v108, v109
	v_max3_f32 v0, v0, v110, v111
	s_mov_b32 s28, 0x41000000
	s_nop 7
	v_max3_f32 v0, v0, v80, v81
	v_max3_f32 v0, v0, v82, v83
	v_max3_f32 v0, v0, v84, v85
	v_max3_f32 v0, v0, v86, v87
	v_max3_f32 v0, v0, v88, v89
	v_max3_f32 v0, v0, v90, v91
	v_max3_f32 v0, v0, v92, v93
	v_max3_f32 v0, v0, v94, v95
	v_mov_b32_e32 v2, v0
	s_nop 1
	v_permlane32_swap_b32_e32 v0, v2
	v_max_f32_e32 v2, v2, v2
	v_max_f32_e32 v0, v0, v0
	v_max_f32_e32 v0, v0, v2
	v_cmp_ge_f32_e32 vcc, s28, v0
	s_cmp_eq_u64 vcc, exec
	s_cbranch_scc1 .LBB0_2906
	v_max_f32_e32 v0, v0, v0
	v_max_f32_e32 v2, 0, v0
	v_exp_f32_e64 v0, -v2
	v_add_f32_e32 v181, v181, v2
	v_sub_f32_e32 v111, v111, v2
	v_sub_f32_e32 v110, v110, v2
	v_pk_mul_f32 v[78:79], v[78:79], v[0:1] op_sel_hi:[1,0]
	v_pk_mul_f32 v[76:77], v[76:77], v[0:1] op_sel_hi:[1,0]
	v_pk_mul_f32 v[74:75], v[74:75], v[0:1] op_sel_hi:[1,0]
	v_pk_mul_f32 v[72:73], v[72:73], v[0:1] op_sel_hi:[1,0]
	v_pk_mul_f32 v[70:71], v[70:71], v[0:1] op_sel_hi:[1,0]
	v_pk_mul_f32 v[68:69], v[68:69], v[0:1] op_sel_hi:[1,0]
	v_pk_mul_f32 v[66:67], v[66:67], v[0:1] op_sel_hi:[1,0]
	v_pk_mul_f32 v[64:65], v[64:65], v[0:1] op_sel_hi:[1,0]
	v_pk_mul_f32 v[62:63], v[62:63], v[0:1] op_sel_hi:[1,0]
	v_pk_mul_f32 v[60:61], v[60:61], v[0:1] op_sel_hi:[1,0]
	v_pk_mul_f32 v[58:59], v[58:59], v[0:1] op_sel_hi:[1,0]
	v_pk_mul_f32 v[56:57], v[56:57], v[0:1] op_sel_hi:[1,0]
	v_pk_mul_f32 v[54:55], v[54:55], v[0:1] op_sel_hi:[1,0]
	v_pk_mul_f32 v[52:53], v[52:53], v[0:1] op_sel_hi:[1,0]
	v_pk_mul_f32 v[50:51], v[50:51], v[0:1] op_sel_hi:[1,0]
	v_pk_mul_f32 v[48:49], v[48:49], v[0:1] op_sel_hi:[1,0]
	v_pk_mul_f32 v[46:47], v[46:47], v[0:1] op_sel_hi:[1,0]
	v_pk_mul_f32 v[44:45], v[44:45], v[0:1] op_sel_hi:[1,0]
	v_pk_mul_f32 v[42:43], v[42:43], v[0:1] op_sel_hi:[1,0]
	v_pk_mul_f32 v[40:41], v[40:41], v[0:1] op_sel_hi:[1,0]
	v_pk_mul_f32 v[38:39], v[38:39], v[0:1] op_sel_hi:[1,0]
	v_pk_mul_f32 v[36:37], v[36:37], v[0:1] op_sel_hi:[1,0]
	v_pk_mul_f32 v[34:35], v[34:35], v[0:1] op_sel_hi:[1,0]
	v_pk_mul_f32 v[32:33], v[32:33], v[0:1] op_sel_hi:[1,0]
	v_pk_mul_f32 v[30:31], v[30:31], v[0:1] op_sel_hi:[1,0]
	v_pk_mul_f32 v[28:29], v[28:29], v[0:1] op_sel_hi:[1,0]
	v_pk_mul_f32 v[26:27], v[26:27], v[0:1] op_sel_hi:[1,0]
	v_pk_mul_f32 v[24:25], v[24:25], v[0:1] op_sel_hi:[1,0]
	v_pk_mul_f32 v[22:23], v[22:23], v[0:1] op_sel_hi:[1,0]
	v_pk_mul_f32 v[20:21], v[20:21], v[0:1] op_sel_hi:[1,0]
	v_pk_mul_f32 v[18:19], v[18:19], v[0:1] op_sel_hi:[1,0]
	v_pk_mul_f32 v[16:17], v[16:17], v[0:1] op_sel_hi:[1,0]
	v_sub_f32_e32 v109, v109, v2
	v_sub_f32_e32 v108, v108, v2
	v_sub_f32_e32 v107, v107, v2
	v_sub_f32_e32 v106, v106, v2
	v_sub_f32_e32 v105, v105, v2
	v_sub_f32_e32 v104, v104, v2
	v_sub_f32_e32 v103, v103, v2
	v_sub_f32_e32 v102, v102, v2
	v_sub_f32_e32 v101, v101, v2
	v_sub_f32_e32 v100, v100, v2
	v_sub_f32_e32 v99, v99, v2
	v_sub_f32_e32 v98, v98, v2
	v_sub_f32_e32 v97, v97, v2
	v_sub_f32_e32 v96, v96, v2
	v_sub_f32_e32 v95, v95, v2
	v_sub_f32_e32 v94, v94, v2
	v_sub_f32_e32 v93, v93, v2
	v_sub_f32_e32 v92, v92, v2
	v_sub_f32_e32 v91, v91, v2
	v_sub_f32_e32 v90, v90, v2
	v_sub_f32_e32 v89, v89, v2
	v_sub_f32_e32 v88, v88, v2
	v_sub_f32_e32 v87, v87, v2
	v_sub_f32_e32 v86, v86, v2
	v_sub_f32_e32 v85, v85, v2
	v_sub_f32_e32 v84, v84, v2
	v_sub_f32_e32 v83, v83, v2
	v_sub_f32_e32 v82, v82, v2
	v_sub_f32_e32 v81, v81, v2
	v_sub_f32_e32 v80, v80, v2
	v_mul_f32_e32 v171, v171, v0
